# P1: x rows of waves 1..7 requested before the P0|P1 flat grid barrier wait (x is an input, independent of P0); all 8 rows of a wave in flight at once
# speedup vs baseline: 1.0075x; 1.0067x over previous
.LBB0_60:
	s_mov_b32 s97, 0
	s_cmp_lt_i32 s57, 2
	s_cbranch_scc1 .LBB0_154
	s_mov_b64 s[4:5], -1
	s_and_b64 vcc, exec, s[62:63]
	s_cbranch_vccz .LBB0_115
	s_waitcnt vmcnt(0)
	s_barrier
	s_and_saveexec_b64 s[4:5], s[58:59]
	s_cbranch_execz .LBB0_114
	s_add_i32 s0, 0, 0x27d60
	v_mov_b32_e32 v2, s0
	s_waitcnt vmcnt(0) expcnt(0) lgkmcnt(0)
	ds_read_b32 v4, v2
	s_add_i32 s0, 0, 0x27d64
	v_mov_b32_e32 v2, s0
	ds_read_b32 v2, v2
	s_waitcnt lgkmcnt(1)
	v_cmp_ne_u32_e32 vcc, 0, v4
	s_cbranch_vccnz .LBB0_78
	v_readlane_b32 s6, v250, 8
	v_readlane_b32 s7, v250, 9
	s_load_dwordx2 s[0:1], s[6:7], 0x4
	s_add_u32 s6, s34, 0x4200
	s_addc_u32 s7, s35, 0
	s_add_u32 s22, s34, 0x4400
	s_addc_u32 s23, s35, 0
	s_add_u32 s24, s34, 0x4500
	s_addc_u32 s25, s35, 0
	s_add_u32 s38, s34, 0x4600
	s_addc_u32 s39, s35, 0
	s_add_u32 s40, s34, 0x4700
	s_addc_u32 s41, s35, 0
	s_add_u32 s42, s34, 0x4800
	s_addc_u32 s43, s35, 0
	s_add_u32 s44, s34, 0x4900
	s_addc_u32 s45, s35, 0
	s_add_u32 s46, s34, 0x4a00
	s_addc_u32 s47, s35, 0
	s_add_u32 s72, s34, 0x4b00
	s_addc_u32 s73, s35, 0
	s_add_u32 s74, s34, 0x4c00
	s_addc_u32 s75, s35, 0
	s_add_u32 s76, s34, 0x4d00
	s_addc_u32 s77, s35, 0
	s_add_u32 s78, s34, 0x4e00
	s_addc_u32 s79, s35, 0
	s_add_u32 s80, s34, 0x4f00
	s_addc_u32 s81, s35, 0
	s_add_u32 s82, s34, 0x5000
	s_addc_u32 s83, s35, 0
	s_add_u32 s84, s34, 0x5100
	s_addc_u32 s85, s35, 0
	s_add_u32 s86, s34, 0x5200
	s_addc_u32 s87, s35, 0
	s_waitcnt lgkmcnt(0)
	s_mul_i32 s0, s0, s33
	s_add_u32 s88, s34, 0x5300
	s_mov_b32 s26, s89
	s_mul_i32 s0, s0, s1
	s_addc_u32 s89, s35, 0
	s_mov_b32 s1, 1
	v_mov_b32_e32 v18, 0
	s_branch .LBB0_66

.Lp1pf:
	s_lshl_b32 s0, s61, 6
	s_lshl_b32 s1, s99, 3
	s_add_i32 s0, s0, s1
	s_ashr_i32 s1, s0, 31
	s_lshl_b64 s[0:1], s[0:1], 12
	s_add_u32 s0, s36, s0
	s_addc_u32 s1, s37, s1
	v_lshlrev_b32_e32 v112, 5, v1
	s_mov_b32 s97, 1
	global_load_dwordx4 v[114:117], v112, s[0:1] nt
	global_load_dwordx4 v[118:121], v112, s[0:1] offset:16 nt
	global_load_dwordx4 v[126:129], v112, s[0:1] offset:2064 nt
	global_load_dwordx4 v[122:125], v112, s[0:1] offset:2048 nt
	s_add_u32 s0, s0, 0x1000
	s_addc_u32 s1, s1, 0
	global_load_dwordx4 v[130:133], v112, s[0:1] nt
	global_load_dwordx4 v[134:137], v112, s[0:1] offset:16 nt
	global_load_dwordx4 v[142:145], v112, s[0:1] offset:2064 nt
	global_load_dwordx4 v[138:141], v112, s[0:1] offset:2048 nt
	s_add_u32 s0, s0, 0x1000
	s_addc_u32 s1, s1, 0
	global_load_dwordx4 v[146:149], v112, s[0:1] nt
	global_load_dwordx4 v[150:153], v112, s[0:1] offset:16 nt
	global_load_dwordx4 v[158:161], v112, s[0:1] offset:2064 nt
	global_load_dwordx4 v[154:157], v112, s[0:1] offset:2048 nt
	s_add_u32 s0, s0, 0x1000
	s_addc_u32 s1, s1, 0
	global_load_dwordx4 v[162:165], v112, s[0:1] nt
	global_load_dwordx4 v[166:169], v112, s[0:1] offset:16 nt
	global_load_dwordx4 v[174:177], v112, s[0:1] offset:2064 nt
	global_load_dwordx4 v[170:173], v112, s[0:1] offset:2048 nt
	s_add_u32 s0, s0, 0x1000
	s_addc_u32 s1, s1, 0
	global_load_dwordx4 v[178:181], v112, s[0:1] nt
	global_load_dwordx4 v[182:185], v112, s[0:1] offset:16 nt
	global_load_dwordx4 v[190:193], v112, s[0:1] offset:2064 nt
	global_load_dwordx4 v[186:189], v112, s[0:1] offset:2048 nt
	s_add_u32 s0, s0, 0x1000
	s_addc_u32 s1, s1, 0
	global_load_dwordx4 v[194:197], v112, s[0:1] nt
	global_load_dwordx4 v[198:201], v112, s[0:1] offset:16 nt
	global_load_dwordx4 v[206:209], v112, s[0:1] offset:2064 nt
	global_load_dwordx4 v[202:205], v112, s[0:1] offset:2048 nt
	s_add_u32 s0, s0, 0x1000
	s_addc_u32 s1, s1, 0
	global_load_dwordx4 v[210:213], v112, s[0:1] nt
	global_load_dwordx4 v[214:217], v112, s[0:1] offset:16 nt
	global_load_dwordx4 v[222:225], v112, s[0:1] offset:2064 nt
	global_load_dwordx4 v[218:221], v112, s[0:1] offset:2048 nt
	s_add_u32 s0, s0, 0x1000
	s_addc_u32 s1, s1, 0
	global_load_dwordx4 v[226:229], v112, s[0:1] nt
	global_load_dwordx4 v[230:233], v112, s[0:1] offset:16 nt
	global_load_dwordx4 v[238:241], v112, s[0:1] offset:2064 nt
	global_load_dwordx4 v[234:237], v112, s[0:1] offset:2048 nt
	s_branch .LBB0_152

.LBB0_157:
	s_ashr_i32 s0, s4, 31
	s_lshr_b32 s0, s0, 21
	s_add_i32 s0, s4, s0
	s_ashr_i32 s0, s0, 11
	s_mul_hi_i32 s7, s0, 0x6000
	s_mulk_i32 s0, 0x6000
	s_add_u32 s26, s52, s0
	s_addc_u32 s27, s53, s7
	v_lshl_add_u64 v[2:3], s[26:27], 0, v[50:51]
	v_add_co_u32_e32 v10, vcc, s5, v2
	v_lshl_add_u64 v[22:23], v[2:3], 0, s[40:41]
	s_nop 0
	v_addc_co_u32_e32 v11, vcc, 0, v3, vcc
	global_load_dwordx4 v[2:5], v50, s[26:27] offset:16
	global_load_dwordx4 v[6:9], v50, s[26:27]
	s_nop 0
	global_load_dwordx4 v[10:13], v[10:11], off
	s_nop 0
	global_load_dwordx4 v[14:17], v[22:23], off offset:2064
	global_load_dwordx4 v[18:21], v[22:23], off offset:16
	s_nop 0
	global_load_dwordx4 v[22:25], v[22:23], off offset:2048
	s_nop 0
	global_load_dwordx4 v[26:29], v50, s[26:27] offset:2064
	global_load_dwordx4 v[30:33], v50, s[26:27] offset:2048
	v_mov_b64_e32 v[62:63], v[60:61]
	v_mov_b64_e32 v[64:65], v[58:59]
	s_mov_b32 s7, 0
	s_mov_b64 s[76:77], 0x800
	s_cmp_eq_u32 s97, 1
	s_cbranch_scc1 .Lp1_pfd
	global_load_dwordx4 v[114:117], v[62:63], off nt
	global_load_dwordx4 v[118:121], v[62:63], off offset:16 nt
	global_load_dwordx4 v[126:129], v[62:63], off offset:2064 nt
	global_load_dwordx4 v[122:125], v[62:63], off offset:2048 nt
	v_lshl_add_u64 v[62:63], v[62:63], 0, s[40:41]
	global_load_dwordx4 v[130:133], v[62:63], off nt
	global_load_dwordx4 v[134:137], v[62:63], off offset:16 nt
	global_load_dwordx4 v[142:145], v[62:63], off offset:2064 nt
	global_load_dwordx4 v[138:141], v[62:63], off offset:2048 nt
	v_lshl_add_u64 v[62:63], v[62:63], 0, s[40:41]
	global_load_dwordx4 v[146:149], v[62:63], off nt
	global_load_dwordx4 v[150:153], v[62:63], off offset:16 nt
	global_load_dwordx4 v[158:161], v[62:63], off offset:2064 nt
	global_load_dwordx4 v[154:157], v[62:63], off offset:2048 nt
	v_lshl_add_u64 v[62:63], v[62:63], 0, s[40:41]
	global_load_dwordx4 v[162:165], v[62:63], off nt
	global_load_dwordx4 v[166:169], v[62:63], off offset:16 nt
	global_load_dwordx4 v[174:177], v[62:63], off offset:2064 nt
	global_load_dwordx4 v[170:173], v[62:63], off offset:2048 nt
	v_lshl_add_u64 v[62:63], v[62:63], 0, s[40:41]
	global_load_dwordx4 v[178:181], v[62:63], off nt
	global_load_dwordx4 v[182:185], v[62:63], off offset:16 nt
	global_load_dwordx4 v[190:193], v[62:63], off offset:2064 nt
	global_load_dwordx4 v[186:189], v[62:63], off offset:2048 nt
	v_lshl_add_u64 v[62:63], v[62:63], 0, s[40:41]
	global_load_dwordx4 v[194:197], v[62:63], off nt
	global_load_dwordx4 v[198:201], v[62:63], off offset:16 nt
	global_load_dwordx4 v[206:209], v[62:63], off offset:2064 nt
	global_load_dwordx4 v[202:205], v[62:63], off offset:2048 nt
	v_lshl_add_u64 v[62:63], v[62:63], 0, s[40:41]
	global_load_dwordx4 v[210:213], v[62:63], off nt
	global_load_dwordx4 v[214:217], v[62:63], off offset:16 nt
	global_load_dwordx4 v[222:225], v[62:63], off offset:2064 nt
	global_load_dwordx4 v[218:221], v[62:63], off offset:2048 nt
	v_lshl_add_u64 v[62:63], v[62:63], 0, s[40:41]
	global_load_dwordx4 v[226:229], v[62:63], off nt
	global_load_dwordx4 v[230:233], v[62:63], off offset:16 nt
	global_load_dwordx4 v[238:241], v[62:63], off offset:2064 nt
	global_load_dwordx4 v[234:237], v[62:63], off offset:2048 nt
	s_branch .Lp1_rows

.Lp1_rows:
	s_waitcnt vmcnt(28)
	v_pk_mul_f32 v[90:91], v[116:117], v[116:117]
	v_pk_mul_f32 v[92:93], v[114:115], v[114:115]
	v_pk_mul_f32 v[100:101], v[120:121], v[120:121]
	v_pk_mul_f32 v[102:103], v[118:119], v[118:119]
	v_pk_mov_b32 v[108:109], v[92:93], v[90:91] op_sel:[1,0]
	v_mov_b32_e32 v93, v91
	v_pk_mov_b32 v[90:91], v[102:103], v[100:101] op_sel:[1,0]
	v_mov_b32_e32 v103, v101
	v_mul_f32_e32 v107, v129, v129
	v_mul_f32_e32 v104, v123, v123
	v_mul_f32_e32 v106, v125, v125
	v_pk_add_f32 v[92:93], v[108:109], v[92:93]
	v_pk_add_f32 v[90:91], v[90:91], v[102:103]
	v_mul_f32_e32 v89, v128, v128
	v_mul_f32_e32 v110, v126, v126
	v_mul_f32_e32 v111, v127, v127
	v_pk_fma_f32 v[100:101], v[122:123], v[122:123], v[104:105] op_sel_hi:[1,1,0]
	v_pk_fma_f32 v[104:105], v[124:125], v[124:125], v[106:107] op_sel_hi:[1,1,0]
	v_pk_add_f32 v[92:93], v[92:93], v[92:93] op_sel:[0,1] op_sel_hi:[1,0]
	v_pk_add_f32 v[90:91], v[90:91], v[90:91] op_sel:[0,1] op_sel_hi:[1,0]
	v_mov_b32_e32 v101, v89
	v_mov_b32_e32 v105, v107
	v_mov_b32_e32 v93, v110
	v_mov_b32_e32 v91, v111
	v_pk_add_f32 v[100:101], v[100:101], v[104:105]
	v_pk_add_f32 v[90:91], v[92:93], v[90:91]
	s_nop 0
	v_pk_add_f32 v[90:91], v[90:91], v[100:101]
	s_nop 0
	v_add_f32_e32 v89, v90, v91
	s_nop 1
	v_add_f32_dpp v89, v89, v89 quad_perm:[1,0,3,2] row_mask:0xf bank_mask:0xf bound_ctrl:1
	s_nop 1
	v_add_f32_dpp v89, v89, v89 quad_perm:[2,3,0,1] row_mask:0xf bank_mask:0xf bound_ctrl:1
	s_nop 1
	v_add_f32_dpp v89, v89, v89 row_half_mirror row_mask:0xf bank_mask:0xf bound_ctrl:1
	s_nop 1
	v_add_f32_dpp v89, v89, v89 row_mirror row_mask:0xf bank_mask:0xf bound_ctrl:1
	s_nop 0
	v_readlane_b32 s0, v89, 16
	v_readlane_b32 s28, v89, 48
	v_readlane_b32 s26, v89, 0
	v_readlane_b32 s27, v89, 32
	v_mov_b32_e32 v90, s0
	v_mov_b32_e32 v91, s28
	v_pk_add_f32 v[90:91], s[26:27], v[90:91]
	s_nop 0
	v_add_f32_e32 v89, v90, v91
	v_fmamk_f32 v89, v89, 0x3a800000, v88
	v_rsq_f32_e32 v90, v89
	v_lshl_add_u64 v[66:67], v[64:65], 0, s[42:43]
	v_pk_mul_f32 v[92:93], v[114:115], v[90:91] op_sel_hi:[1,0]
	v_pk_mul_f32 v[100:101], v[116:117], v[90:91] op_sel_hi:[1,0]
	v_pk_mul_f32 v[102:103], v[118:119], v[90:91] op_sel_hi:[1,0]
	v_pk_mul_f32 v[104:105], v[120:121], v[90:91] op_sel_hi:[1,0]
	v_pk_mul_f32 v[106:107], v[122:123], v[90:91] op_sel_hi:[1,0]
	v_pk_mul_f32 v[108:109], v[124:125], v[90:91] op_sel_hi:[1,0]
	v_pk_mul_f32 v[110:111], v[126:127], v[90:91] op_sel_hi:[1,0]
	v_pk_mul_f32 v[90:91], v[128:129], v[90:91] op_sel_hi:[1,0]
	v_pk_fma_f32 v[92:93], v[10:11], v[92:93], v[6:7]
	v_pk_fma_f32 v[100:101], v[12:13], v[100:101], v[8:9]
	v_pk_fma_f32 v[102:103], v[18:19], v[102:103], v[2:3]
	v_pk_fma_f32 v[104:105], v[20:21], v[104:105], v[4:5]
	v_pk_fma_f32 v[108:109], v[24:25], v[108:109], v[32:33]
	v_pk_fma_f32 v[106:107], v[22:23], v[106:107], v[30:31]
	v_pk_fma_f32 v[112:113], v[16:17], v[90:91], v[28:29]
	v_pk_fma_f32 v[110:111], v[14:15], v[110:111], v[26:27]
	v_cvt_pk_bf16_f32 v90, v92, v93
	v_cvt_pk_bf16_f32 v91, v100, v101
	v_cvt_pk_bf16_f32 v92, v102, v103
	v_cvt_pk_bf16_f32 v93, v104, v105
	s_nop 0
	global_store_dwordx4 v[66:67], v[90:93], off sc1
	s_nop 1
	v_cvt_pk_bf16_f32 v114, v114, v115
	v_cvt_pk_bf16_f32 v115, v116, v117
	v_cvt_pk_bf16_f32 v116, v118, v119
	v_cvt_pk_bf16_f32 v117, v120, v121
	v_lshl_add_u64 v[68:69], v[64:65], 0, s[44:45]
	global_store_dwordx4 v[64:65], v[114:117], off sc1
	s_nop 1
	v_cvt_pk_bf16_f32 v34, v106, v107
	v_cvt_pk_bf16_f32 v35, v108, v109
	v_cvt_pk_bf16_f32 v36, v110, v111
	v_cvt_pk_bf16_f32 v37, v112, v113
	v_lshl_add_u64 v[70:71], v[64:65], 0, s[46:47]
	global_store_dwordx4 v[68:69], v[34:37], off sc1
	s_nop 1
	v_cvt_pk_bf16_f32 v122, v122, v123
	v_cvt_pk_bf16_f32 v123, v124, v125
	v_cvt_pk_bf16_f32 v124, v126, v127
	v_cvt_pk_bf16_f32 v125, v128, v129
	s_nop 0
	global_store_dwordx4 v[70:71], v[122:125], off sc1
	s_nop 1
	v_lshl_add_u64 v[64:65], v[64:65], 0, s[76:77]
	s_waitcnt vmcnt(28)
	v_pk_mul_f32 v[90:91], v[132:133], v[132:133]
	v_pk_mul_f32 v[92:93], v[130:131], v[130:131]
	v_pk_mul_f32 v[100:101], v[136:137], v[136:137]
	v_pk_mul_f32 v[102:103], v[134:135], v[134:135]
	v_pk_mov_b32 v[108:109], v[92:93], v[90:91] op_sel:[1,0]
	v_mov_b32_e32 v93, v91
	v_pk_mov_b32 v[90:91], v[102:103], v[100:101] op_sel:[1,0]
	v_mov_b32_e32 v103, v101
	v_mul_f32_e32 v107, v145, v145
	v_mul_f32_e32 v104, v139, v139
	v_mul_f32_e32 v106, v141, v141
	v_pk_add_f32 v[92:93], v[108:109], v[92:93]
	v_pk_add_f32 v[90:91], v[90:91], v[102:103]
	v_mul_f32_e32 v89, v144, v144
	v_mul_f32_e32 v110, v142, v142
	v_mul_f32_e32 v111, v143, v143
	v_pk_fma_f32 v[100:101], v[138:139], v[138:139], v[104:105] op_sel_hi:[1,1,0]
	v_pk_fma_f32 v[104:105], v[140:141], v[140:141], v[106:107] op_sel_hi:[1,1,0]
	v_pk_add_f32 v[92:93], v[92:93], v[92:93] op_sel:[0,1] op_sel_hi:[1,0]
	v_pk_add_f32 v[90:91], v[90:91], v[90:91] op_sel:[0,1] op_sel_hi:[1,0]
	v_mov_b32_e32 v101, v89
	v_mov_b32_e32 v105, v107
	v_mov_b32_e32 v93, v110
	v_mov_b32_e32 v91, v111
	v_pk_add_f32 v[100:101], v[100:101], v[104:105]
	v_pk_add_f32 v[90:91], v[92:93], v[90:91]
	s_nop 0
	v_pk_add_f32 v[90:91], v[90:91], v[100:101]
	s_nop 0
	v_add_f32_e32 v89, v90, v91
	s_nop 1
	v_add_f32_dpp v89, v89, v89 quad_perm:[1,0,3,2] row_mask:0xf bank_mask:0xf bound_ctrl:1
	s_nop 1
	v_add_f32_dpp v89, v89, v89 quad_perm:[2,3,0,1] row_mask:0xf bank_mask:0xf bound_ctrl:1
	s_nop 1
	v_add_f32_dpp v89, v89, v89 row_half_mirror row_mask:0xf bank_mask:0xf bound_ctrl:1
	s_nop 1
	v_add_f32_dpp v89, v89, v89 row_mirror row_mask:0xf bank_mask:0xf bound_ctrl:1
	s_nop 0
	v_readlane_b32 s0, v89, 16
	v_readlane_b32 s28, v89, 48
	v_readlane_b32 s26, v89, 0
	v_readlane_b32 s27, v89, 32
	v_mov_b32_e32 v90, s0
	v_mov_b32_e32 v91, s28
	v_pk_add_f32 v[90:91], s[26:27], v[90:91]
	s_nop 0
	v_add_f32_e32 v89, v90, v91
	v_fmamk_f32 v89, v89, 0x3a800000, v88
	v_rsq_f32_e32 v90, v89
	v_lshl_add_u64 v[66:67], v[64:65], 0, s[42:43]
	v_pk_mul_f32 v[92:93], v[130:131], v[90:91] op_sel_hi:[1,0]
	v_pk_mul_f32 v[100:101], v[132:133], v[90:91] op_sel_hi:[1,0]
	v_pk_mul_f32 v[102:103], v[134:135], v[90:91] op_sel_hi:[1,0]
	v_pk_mul_f32 v[104:105], v[136:137], v[90:91] op_sel_hi:[1,0]
	v_pk_mul_f32 v[106:107], v[138:139], v[90:91] op_sel_hi:[1,0]
	v_pk_mul_f32 v[108:109], v[140:141], v[90:91] op_sel_hi:[1,0]
	v_pk_mul_f32 v[110:111], v[142:143], v[90:91] op_sel_hi:[1,0]
	v_pk_mul_f32 v[90:91], v[144:145], v[90:91] op_sel_hi:[1,0]
	v_pk_fma_f32 v[92:93], v[10:11], v[92:93], v[6:7]
	v_pk_fma_f32 v[100:101], v[12:13], v[100:101], v[8:9]
	v_pk_fma_f32 v[102:103], v[18:19], v[102:103], v[2:3]
	v_pk_fma_f32 v[104:105], v[20:21], v[104:105], v[4:5]
	v_pk_fma_f32 v[108:109], v[24:25], v[108:109], v[32:33]
	v_pk_fma_f32 v[106:107], v[22:23], v[106:107], v[30:31]
	v_pk_fma_f32 v[112:113], v[16:17], v[90:91], v[28:29]
	v_pk_fma_f32 v[110:111], v[14:15], v[110:111], v[26:27]
	v_cvt_pk_bf16_f32 v90, v92, v93
	v_cvt_pk_bf16_f32 v91, v100, v101
	v_cvt_pk_bf16_f32 v92, v102, v103
	v_cvt_pk_bf16_f32 v93, v104, v105
	s_nop 0
	global_store_dwordx4 v[66:67], v[90:93], off sc1
	s_nop 1
	v_cvt_pk_bf16_f32 v130, v130, v131
	v_cvt_pk_bf16_f32 v131, v132, v133
	v_cvt_pk_bf16_f32 v132, v134, v135
	v_cvt_pk_bf16_f32 v133, v136, v137
	v_lshl_add_u64 v[68:69], v[64:65], 0, s[44:45]
	global_store_dwordx4 v[64:65], v[130:133], off sc1
	s_nop 1
	v_cvt_pk_bf16_f32 v34, v106, v107
	v_cvt_pk_bf16_f32 v35, v108, v109
	v_cvt_pk_bf16_f32 v36, v110, v111
	v_cvt_pk_bf16_f32 v37, v112, v113
	v_lshl_add_u64 v[70:71], v[64:65], 0, s[46:47]
	global_store_dwordx4 v[68:69], v[34:37], off sc1
	s_nop 1
	v_cvt_pk_bf16_f32 v138, v138, v139
	v_cvt_pk_bf16_f32 v139, v140, v141
	v_cvt_pk_bf16_f32 v140, v142, v143
	v_cvt_pk_bf16_f32 v141, v144, v145
	s_nop 0
	global_store_dwordx4 v[70:71], v[138:141], off sc1
	s_nop 1
	v_lshl_add_u64 v[64:65], v[64:65], 0, s[76:77]
	s_waitcnt vmcnt(28)
	v_pk_mul_f32 v[90:91], v[148:149], v[148:149]
	v_pk_mul_f32 v[92:93], v[146:147], v[146:147]
	v_pk_mul_f32 v[100:101], v[152:153], v[152:153]
	v_pk_mul_f32 v[102:103], v[150:151], v[150:151]
	v_pk_mov_b32 v[108:109], v[92:93], v[90:91] op_sel:[1,0]
	v_mov_b32_e32 v93, v91
	v_pk_mov_b32 v[90:91], v[102:103], v[100:101] op_sel:[1,0]
	v_mov_b32_e32 v103, v101
	v_mul_f32_e32 v107, v161, v161
	v_mul_f32_e32 v104, v155, v155
	v_mul_f32_e32 v106, v157, v157
	v_pk_add_f32 v[92:93], v[108:109], v[92:93]
	v_pk_add_f32 v[90:91], v[90:91], v[102:103]
	v_mul_f32_e32 v89, v160, v160
	v_mul_f32_e32 v110, v158, v158
	v_mul_f32_e32 v111, v159, v159
	v_pk_fma_f32 v[100:101], v[154:155], v[154:155], v[104:105] op_sel_hi:[1,1,0]
	v_pk_fma_f32 v[104:105], v[156:157], v[156:157], v[106:107] op_sel_hi:[1,1,0]
	v_pk_add_f32 v[92:93], v[92:93], v[92:93] op_sel:[0,1] op_sel_hi:[1,0]
	v_pk_add_f32 v[90:91], v[90:91], v[90:91] op_sel:[0,1] op_sel_hi:[1,0]
	v_mov_b32_e32 v101, v89
	v_mov_b32_e32 v105, v107
	v_mov_b32_e32 v93, v110
	v_mov_b32_e32 v91, v111
	v_pk_add_f32 v[100:101], v[100:101], v[104:105]
	v_pk_add_f32 v[90:91], v[92:93], v[90:91]
	s_nop 0
	v_pk_add_f32 v[90:91], v[90:91], v[100:101]
	s_nop 0
	v_add_f32_e32 v89, v90, v91
	s_nop 1
	v_add_f32_dpp v89, v89, v89 quad_perm:[1,0,3,2] row_mask:0xf bank_mask:0xf bound_ctrl:1
	s_nop 1
	v_add_f32_dpp v89, v89, v89 quad_perm:[2,3,0,1] row_mask:0xf bank_mask:0xf bound_ctrl:1
	s_nop 1
	v_add_f32_dpp v89, v89, v89 row_half_mirror row_mask:0xf bank_mask:0xf bound_ctrl:1
	s_nop 1
	v_add_f32_dpp v89, v89, v89 row_mirror row_mask:0xf bank_mask:0xf bound_ctrl:1
	s_nop 0
	v_readlane_b32 s0, v89, 16
	v_readlane_b32 s28, v89, 48
	v_readlane_b32 s26, v89, 0
	v_readlane_b32 s27, v89, 32
	v_mov_b32_e32 v90, s0
	v_mov_b32_e32 v91, s28
	v_pk_add_f32 v[90:91], s[26:27], v[90:91]
	s_nop 0
	v_add_f32_e32 v89, v90, v91
	v_fmamk_f32 v89, v89, 0x3a800000, v88
	v_rsq_f32_e32 v90, v89
	v_lshl_add_u64 v[66:67], v[64:65], 0, s[42:43]
	v_pk_mul_f32 v[92:93], v[146:147], v[90:91] op_sel_hi:[1,0]
	v_pk_mul_f32 v[100:101], v[148:149], v[90:91] op_sel_hi:[1,0]
	v_pk_mul_f32 v[102:103], v[150:151], v[90:91] op_sel_hi:[1,0]
	v_pk_mul_f32 v[104:105], v[152:153], v[90:91] op_sel_hi:[1,0]
	v_pk_mul_f32 v[106:107], v[154:155], v[90:91] op_sel_hi:[1,0]
	v_pk_mul_f32 v[108:109], v[156:157], v[90:91] op_sel_hi:[1,0]
	v_pk_mul_f32 v[110:111], v[158:159], v[90:91] op_sel_hi:[1,0]
	v_pk_mul_f32 v[90:91], v[160:161], v[90:91] op_sel_hi:[1,0]
	v_pk_fma_f32 v[92:93], v[10:11], v[92:93], v[6:7]
	v_pk_fma_f32 v[100:101], v[12:13], v[100:101], v[8:9]
	v_pk_fma_f32 v[102:103], v[18:19], v[102:103], v[2:3]
	v_pk_fma_f32 v[104:105], v[20:21], v[104:105], v[4:5]
	v_pk_fma_f32 v[108:109], v[24:25], v[108:109], v[32:33]
	v_pk_fma_f32 v[106:107], v[22:23], v[106:107], v[30:31]
	v_pk_fma_f32 v[112:113], v[16:17], v[90:91], v[28:29]
	v_pk_fma_f32 v[110:111], v[14:15], v[110:111], v[26:27]
	v_cvt_pk_bf16_f32 v90, v92, v93
	v_cvt_pk_bf16_f32 v91, v100, v101
	v_cvt_pk_bf16_f32 v92, v102, v103
	v_cvt_pk_bf16_f32 v93, v104, v105
	s_nop 0
	global_store_dwordx4 v[66:67], v[90:93], off sc1
	s_nop 1
	v_cvt_pk_bf16_f32 v146, v146, v147
	v_cvt_pk_bf16_f32 v147, v148, v149
	v_cvt_pk_bf16_f32 v148, v150, v151
	v_cvt_pk_bf16_f32 v149, v152, v153
	v_lshl_add_u64 v[68:69], v[64:65], 0, s[44:45]
	global_store_dwordx4 v[64:65], v[146:149], off sc1
	s_nop 1
	v_cvt_pk_bf16_f32 v34, v106, v107
	v_cvt_pk_bf16_f32 v35, v108, v109
	v_cvt_pk_bf16_f32 v36, v110, v111
	v_cvt_pk_bf16_f32 v37, v112, v113
	v_lshl_add_u64 v[70:71], v[64:65], 0, s[46:47]
	global_store_dwordx4 v[68:69], v[34:37], off sc1
	s_nop 1
	v_cvt_pk_bf16_f32 v154, v154, v155
	v_cvt_pk_bf16_f32 v155, v156, v157
	v_cvt_pk_bf16_f32 v156, v158, v159
	v_cvt_pk_bf16_f32 v157, v160, v161
	s_nop 0
	global_store_dwordx4 v[70:71], v[154:157], off sc1
	s_nop 1
	v_lshl_add_u64 v[64:65], v[64:65], 0, s[76:77]
	s_waitcnt vmcnt(28)
	v_pk_mul_f32 v[90:91], v[164:165], v[164:165]
	v_pk_mul_f32 v[92:93], v[162:163], v[162:163]
	v_pk_mul_f32 v[100:101], v[168:169], v[168:169]
	v_pk_mul_f32 v[102:103], v[166:167], v[166:167]
	v_pk_mov_b32 v[108:109], v[92:93], v[90:91] op_sel:[1,0]
	v_mov_b32_e32 v93, v91
	v_pk_mov_b32 v[90:91], v[102:103], v[100:101] op_sel:[1,0]
	v_mov_b32_e32 v103, v101
	v_mul_f32_e32 v107, v177, v177
	v_mul_f32_e32 v104, v171, v171
	v_mul_f32_e32 v106, v173, v173
	v_pk_add_f32 v[92:93], v[108:109], v[92:93]
	v_pk_add_f32 v[90:91], v[90:91], v[102:103]
	v_mul_f32_e32 v89, v176, v176
	v_mul_f32_e32 v110, v174, v174
	v_mul_f32_e32 v111, v175, v175
	v_pk_fma_f32 v[100:101], v[170:171], v[170:171], v[104:105] op_sel_hi:[1,1,0]
	v_pk_fma_f32 v[104:105], v[172:173], v[172:173], v[106:107] op_sel_hi:[1,1,0]
	v_pk_add_f32 v[92:93], v[92:93], v[92:93] op_sel:[0,1] op_sel_hi:[1,0]
	v_pk_add_f32 v[90:91], v[90:91], v[90:91] op_sel:[0,1] op_sel_hi:[1,0]
	v_mov_b32_e32 v101, v89
	v_mov_b32_e32 v105, v107
	v_mov_b32_e32 v93, v110
	v_mov_b32_e32 v91, v111
	v_pk_add_f32 v[100:101], v[100:101], v[104:105]
	v_pk_add_f32 v[90:91], v[92:93], v[90:91]
	s_nop 0
	v_pk_add_f32 v[90:91], v[90:91], v[100:101]
	s_nop 0
	v_add_f32_e32 v89, v90, v91
	s_nop 1
	v_add_f32_dpp v89, v89, v89 quad_perm:[1,0,3,2] row_mask:0xf bank_mask:0xf bound_ctrl:1
	s_nop 1
	v_add_f32_dpp v89, v89, v89 quad_perm:[2,3,0,1] row_mask:0xf bank_mask:0xf bound_ctrl:1
	s_nop 1
	v_add_f32_dpp v89, v89, v89 row_half_mirror row_mask:0xf bank_mask:0xf bound_ctrl:1
	s_nop 1
	v_add_f32_dpp v89, v89, v89 row_mirror row_mask:0xf bank_mask:0xf bound_ctrl:1
	s_nop 0
	v_readlane_b32 s0, v89, 16
	v_readlane_b32 s28, v89, 48
	v_readlane_b32 s26, v89, 0
	v_readlane_b32 s27, v89, 32
	v_mov_b32_e32 v90, s0
	v_mov_b32_e32 v91, s28
	v_pk_add_f32 v[90:91], s[26:27], v[90:91]
	s_nop 0
	v_add_f32_e32 v89, v90, v91
	v_fmamk_f32 v89, v89, 0x3a800000, v88
	v_rsq_f32_e32 v90, v89
	v_lshl_add_u64 v[66:67], v[64:65], 0, s[42:43]
	v_pk_mul_f32 v[92:93], v[162:163], v[90:91] op_sel_hi:[1,0]
	v_pk_mul_f32 v[100:101], v[164:165], v[90:91] op_sel_hi:[1,0]
	v_pk_mul_f32 v[102:103], v[166:167], v[90:91] op_sel_hi:[1,0]
	v_pk_mul_f32 v[104:105], v[168:169], v[90:91] op_sel_hi:[1,0]
	v_pk_mul_f32 v[106:107], v[170:171], v[90:91] op_sel_hi:[1,0]
	v_pk_mul_f32 v[108:109], v[172:173], v[90:91] op_sel_hi:[1,0]
	v_pk_mul_f32 v[110:111], v[174:175], v[90:91] op_sel_hi:[1,0]
	v_pk_mul_f32 v[90:91], v[176:177], v[90:91] op_sel_hi:[1,0]
	v_pk_fma_f32 v[92:93], v[10:11], v[92:93], v[6:7]
	v_pk_fma_f32 v[100:101], v[12:13], v[100:101], v[8:9]
	v_pk_fma_f32 v[102:103], v[18:19], v[102:103], v[2:3]
	v_pk_fma_f32 v[104:105], v[20:21], v[104:105], v[4:5]
	v_pk_fma_f32 v[108:109], v[24:25], v[108:109], v[32:33]
	v_pk_fma_f32 v[106:107], v[22:23], v[106:107], v[30:31]
	v_pk_fma_f32 v[112:113], v[16:17], v[90:91], v[28:29]
	v_pk_fma_f32 v[110:111], v[14:15], v[110:111], v[26:27]
	v_cvt_pk_bf16_f32 v90, v92, v93
	v_cvt_pk_bf16_f32 v91, v100, v101
	v_cvt_pk_bf16_f32 v92, v102, v103
	v_cvt_pk_bf16_f32 v93, v104, v105
	s_nop 0
	global_store_dwordx4 v[66:67], v[90:93], off sc1
	s_nop 1
	v_cvt_pk_bf16_f32 v162, v162, v163
	v_cvt_pk_bf16_f32 v163, v164, v165
	v_cvt_pk_bf16_f32 v164, v166, v167
	v_cvt_pk_bf16_f32 v165, v168, v169
	v_lshl_add_u64 v[68:69], v[64:65], 0, s[44:45]
	global_store_dwordx4 v[64:65], v[162:165], off sc1
	s_nop 1
	v_cvt_pk_bf16_f32 v34, v106, v107
	v_cvt_pk_bf16_f32 v35, v108, v109
	v_cvt_pk_bf16_f32 v36, v110, v111
	v_cvt_pk_bf16_f32 v37, v112, v113
	v_lshl_add_u64 v[70:71], v[64:65], 0, s[46:47]
	global_store_dwordx4 v[68:69], v[34:37], off sc1
	s_nop 1
	v_cvt_pk_bf16_f32 v170, v170, v171
	v_cvt_pk_bf16_f32 v171, v172, v173
	v_cvt_pk_bf16_f32 v172, v174, v175
	v_cvt_pk_bf16_f32 v173, v176, v177
	s_nop 0
	global_store_dwordx4 v[70:71], v[170:173], off sc1
	s_nop 1
	v_lshl_add_u64 v[64:65], v[64:65], 0, s[76:77]
	s_waitcnt vmcnt(28)
	v_pk_mul_f32 v[90:91], v[180:181], v[180:181]
	v_pk_mul_f32 v[92:93], v[178:179], v[178:179]
	v_pk_mul_f32 v[100:101], v[184:185], v[184:185]
	v_pk_mul_f32 v[102:103], v[182:183], v[182:183]
	v_pk_mov_b32 v[108:109], v[92:93], v[90:91] op_sel:[1,0]
	v_mov_b32_e32 v93, v91
	v_pk_mov_b32 v[90:91], v[102:103], v[100:101] op_sel:[1,0]
	v_mov_b32_e32 v103, v101
	v_mul_f32_e32 v107, v193, v193
	v_mul_f32_e32 v104, v187, v187
	v_mul_f32_e32 v106, v189, v189
	v_pk_add_f32 v[92:93], v[108:109], v[92:93]
	v_pk_add_f32 v[90:91], v[90:91], v[102:103]
	v_mul_f32_e32 v89, v192, v192
	v_mul_f32_e32 v110, v190, v190
	v_mul_f32_e32 v111, v191, v191
	v_pk_fma_f32 v[100:101], v[186:187], v[186:187], v[104:105] op_sel_hi:[1,1,0]
	v_pk_fma_f32 v[104:105], v[188:189], v[188:189], v[106:107] op_sel_hi:[1,1,0]
	v_pk_add_f32 v[92:93], v[92:93], v[92:93] op_sel:[0,1] op_sel_hi:[1,0]
	v_pk_add_f32 v[90:91], v[90:91], v[90:91] op_sel:[0,1] op_sel_hi:[1,0]
	v_mov_b32_e32 v101, v89
	v_mov_b32_e32 v105, v107
	v_mov_b32_e32 v93, v110
	v_mov_b32_e32 v91, v111
	v_pk_add_f32 v[100:101], v[100:101], v[104:105]
	v_pk_add_f32 v[90:91], v[92:93], v[90:91]
	s_nop 0
	v_pk_add_f32 v[90:91], v[90:91], v[100:101]
	s_nop 0
	v_add_f32_e32 v89, v90, v91
	s_nop 1
	v_add_f32_dpp v89, v89, v89 quad_perm:[1,0,3,2] row_mask:0xf bank_mask:0xf bound_ctrl:1
	s_nop 1
	v_add_f32_dpp v89, v89, v89 quad_perm:[2,3,0,1] row_mask:0xf bank_mask:0xf bound_ctrl:1
	s_nop 1
	v_add_f32_dpp v89, v89, v89 row_half_mirror row_mask:0xf bank_mask:0xf bound_ctrl:1
	s_nop 1
	v_add_f32_dpp v89, v89, v89 row_mirror row_mask:0xf bank_mask:0xf bound_ctrl:1
	s_nop 0
	v_readlane_b32 s0, v89, 16
	v_readlane_b32 s28, v89, 48
	v_readlane_b32 s26, v89, 0
	v_readlane_b32 s27, v89, 32
	v_mov_b32_e32 v90, s0
	v_mov_b32_e32 v91, s28
	v_pk_add_f32 v[90:91], s[26:27], v[90:91]
	s_nop 0
	v_add_f32_e32 v89, v90, v91
	v_fmamk_f32 v89, v89, 0x3a800000, v88
	v_rsq_f32_e32 v90, v89
	v_lshl_add_u64 v[66:67], v[64:65], 0, s[42:43]
	v_pk_mul_f32 v[92:93], v[178:179], v[90:91] op_sel_hi:[1,0]
	v_pk_mul_f32 v[100:101], v[180:181], v[90:91] op_sel_hi:[1,0]
	v_pk_mul_f32 v[102:103], v[182:183], v[90:91] op_sel_hi:[1,0]
	v_pk_mul_f32 v[104:105], v[184:185], v[90:91] op_sel_hi:[1,0]
	v_pk_mul_f32 v[106:107], v[186:187], v[90:91] op_sel_hi:[1,0]
	v_pk_mul_f32 v[108:109], v[188:189], v[90:91] op_sel_hi:[1,0]
	v_pk_mul_f32 v[110:111], v[190:191], v[90:91] op_sel_hi:[1,0]
	v_pk_mul_f32 v[90:91], v[192:193], v[90:91] op_sel_hi:[1,0]
	v_pk_fma_f32 v[92:93], v[10:11], v[92:93], v[6:7]
	v_pk_fma_f32 v[100:101], v[12:13], v[100:101], v[8:9]
	v_pk_fma_f32 v[102:103], v[18:19], v[102:103], v[2:3]
	v_pk_fma_f32 v[104:105], v[20:21], v[104:105], v[4:5]
	v_pk_fma_f32 v[108:109], v[24:25], v[108:109], v[32:33]
	v_pk_fma_f32 v[106:107], v[22:23], v[106:107], v[30:31]
	v_pk_fma_f32 v[112:113], v[16:17], v[90:91], v[28:29]
	v_pk_fma_f32 v[110:111], v[14:15], v[110:111], v[26:27]
	v_cvt_pk_bf16_f32 v90, v92, v93
	v_cvt_pk_bf16_f32 v91, v100, v101
	v_cvt_pk_bf16_f32 v92, v102, v103
	v_cvt_pk_bf16_f32 v93, v104, v105
	s_nop 0
	global_store_dwordx4 v[66:67], v[90:93], off sc1
	s_nop 1
	v_cvt_pk_bf16_f32 v178, v178, v179
	v_cvt_pk_bf16_f32 v179, v180, v181
	v_cvt_pk_bf16_f32 v180, v182, v183
	v_cvt_pk_bf16_f32 v181, v184, v185
	v_lshl_add_u64 v[68:69], v[64:65], 0, s[44:45]
	global_store_dwordx4 v[64:65], v[178:181], off sc1
	s_nop 1
	v_cvt_pk_bf16_f32 v34, v106, v107
	v_cvt_pk_bf16_f32 v35, v108, v109
	v_cvt_pk_bf16_f32 v36, v110, v111
	v_cvt_pk_bf16_f32 v37, v112, v113
	v_lshl_add_u64 v[70:71], v[64:65], 0, s[46:47]
	global_store_dwordx4 v[68:69], v[34:37], off sc1
	s_nop 1
	v_cvt_pk_bf16_f32 v186, v186, v187
	v_cvt_pk_bf16_f32 v187, v188, v189
	v_cvt_pk_bf16_f32 v188, v190, v191
	v_cvt_pk_bf16_f32 v189, v192, v193
	s_nop 0
	global_store_dwordx4 v[70:71], v[186:189], off sc1
	s_nop 1
	v_lshl_add_u64 v[64:65], v[64:65], 0, s[76:77]
	s_waitcnt vmcnt(28)
	v_pk_mul_f32 v[90:91], v[196:197], v[196:197]
	v_pk_mul_f32 v[92:93], v[194:195], v[194:195]
	v_pk_mul_f32 v[100:101], v[200:201], v[200:201]
	v_pk_mul_f32 v[102:103], v[198:199], v[198:199]
	v_pk_mov_b32 v[108:109], v[92:93], v[90:91] op_sel:[1,0]
	v_mov_b32_e32 v93, v91
	v_pk_mov_b32 v[90:91], v[102:103], v[100:101] op_sel:[1,0]
	v_mov_b32_e32 v103, v101
	v_mul_f32_e32 v107, v209, v209
	v_mul_f32_e32 v104, v203, v203
	v_mul_f32_e32 v106, v205, v205
	v_pk_add_f32 v[92:93], v[108:109], v[92:93]
	v_pk_add_f32 v[90:91], v[90:91], v[102:103]
	v_mul_f32_e32 v89, v208, v208
	v_mul_f32_e32 v110, v206, v206
	v_mul_f32_e32 v111, v207, v207
	v_pk_fma_f32 v[100:101], v[202:203], v[202:203], v[104:105] op_sel_hi:[1,1,0]
	v_pk_fma_f32 v[104:105], v[204:205], v[204:205], v[106:107] op_sel_hi:[1,1,0]
	v_pk_add_f32 v[92:93], v[92:93], v[92:93] op_sel:[0,1] op_sel_hi:[1,0]
	v_pk_add_f32 v[90:91], v[90:91], v[90:91] op_sel:[0,1] op_sel_hi:[1,0]
	v_mov_b32_e32 v101, v89
	v_mov_b32_e32 v105, v107
	v_mov_b32_e32 v93, v110
	v_mov_b32_e32 v91, v111
	v_pk_add_f32 v[100:101], v[100:101], v[104:105]
	v_pk_add_f32 v[90:91], v[92:93], v[90:91]
	s_nop 0
	v_pk_add_f32 v[90:91], v[90:91], v[100:101]
	s_nop 0
	v_add_f32_e32 v89, v90, v91
	s_nop 1
	v_add_f32_dpp v89, v89, v89 quad_perm:[1,0,3,2] row_mask:0xf bank_mask:0xf bound_ctrl:1
	s_nop 1
	v_add_f32_dpp v89, v89, v89 quad_perm:[2,3,0,1] row_mask:0xf bank_mask:0xf bound_ctrl:1
	s_nop 1
	v_add_f32_dpp v89, v89, v89 row_half_mirror row_mask:0xf bank_mask:0xf bound_ctrl:1
	s_nop 1
	v_add_f32_dpp v89, v89, v89 row_mirror row_mask:0xf bank_mask:0xf bound_ctrl:1
	s_nop 0
	v_readlane_b32 s0, v89, 16
	v_readlane_b32 s28, v89, 48
	v_readlane_b32 s26, v89, 0
	v_readlane_b32 s27, v89, 32
	v_mov_b32_e32 v90, s0
	v_mov_b32_e32 v91, s28
	v_pk_add_f32 v[90:91], s[26:27], v[90:91]
	s_nop 0
	v_add_f32_e32 v89, v90, v91
	v_fmamk_f32 v89, v89, 0x3a800000, v88
	v_rsq_f32_e32 v90, v89
	v_lshl_add_u64 v[66:67], v[64:65], 0, s[42:43]
	v_pk_mul_f32 v[92:93], v[194:195], v[90:91] op_sel_hi:[1,0]
	v_pk_mul_f32 v[100:101], v[196:197], v[90:91] op_sel_hi:[1,0]
	v_pk_mul_f32 v[102:103], v[198:199], v[90:91] op_sel_hi:[1,0]
	v_pk_mul_f32 v[104:105], v[200:201], v[90:91] op_sel_hi:[1,0]
	v_pk_mul_f32 v[106:107], v[202:203], v[90:91] op_sel_hi:[1,0]
	v_pk_mul_f32 v[108:109], v[204:205], v[90:91] op_sel_hi:[1,0]
	v_pk_mul_f32 v[110:111], v[206:207], v[90:91] op_sel_hi:[1,0]
	v_pk_mul_f32 v[90:91], v[208:209], v[90:91] op_sel_hi:[1,0]
	v_pk_fma_f32 v[92:93], v[10:11], v[92:93], v[6:7]
	v_pk_fma_f32 v[100:101], v[12:13], v[100:101], v[8:9]
	v_pk_fma_f32 v[102:103], v[18:19], v[102:103], v[2:3]
	v_pk_fma_f32 v[104:105], v[20:21], v[104:105], v[4:5]
	v_pk_fma_f32 v[108:109], v[24:25], v[108:109], v[32:33]
	v_pk_fma_f32 v[106:107], v[22:23], v[106:107], v[30:31]
	v_pk_fma_f32 v[112:113], v[16:17], v[90:91], v[28:29]
	v_pk_fma_f32 v[110:111], v[14:15], v[110:111], v[26:27]
	v_cvt_pk_bf16_f32 v90, v92, v93
	v_cvt_pk_bf16_f32 v91, v100, v101
	v_cvt_pk_bf16_f32 v92, v102, v103
	v_cvt_pk_bf16_f32 v93, v104, v105
	s_nop 0
	global_store_dwordx4 v[66:67], v[90:93], off sc1
	s_nop 1
	v_cvt_pk_bf16_f32 v194, v194, v195
	v_cvt_pk_bf16_f32 v195, v196, v197
	v_cvt_pk_bf16_f32 v196, v198, v199
	v_cvt_pk_bf16_f32 v197, v200, v201
	v_lshl_add_u64 v[68:69], v[64:65], 0, s[44:45]
	global_store_dwordx4 v[64:65], v[194:197], off sc1
	s_nop 1
	v_cvt_pk_bf16_f32 v34, v106, v107
	v_cvt_pk_bf16_f32 v35, v108, v109
	v_cvt_pk_bf16_f32 v36, v110, v111
	v_cvt_pk_bf16_f32 v37, v112, v113
	v_lshl_add_u64 v[70:71], v[64:65], 0, s[46:47]
	global_store_dwordx4 v[68:69], v[34:37], off sc1
	s_nop 1
	v_cvt_pk_bf16_f32 v202, v202, v203
	v_cvt_pk_bf16_f32 v203, v204, v205
	v_cvt_pk_bf16_f32 v204, v206, v207
	v_cvt_pk_bf16_f32 v205, v208, v209
	s_nop 0
	global_store_dwordx4 v[70:71], v[202:205], off sc1
	s_nop 1
	v_lshl_add_u64 v[64:65], v[64:65], 0, s[76:77]
	s_waitcnt vmcnt(28)
	v_pk_mul_f32 v[90:91], v[212:213], v[212:213]
	v_pk_mul_f32 v[92:93], v[210:211], v[210:211]
	v_pk_mul_f32 v[100:101], v[216:217], v[216:217]
	v_pk_mul_f32 v[102:103], v[214:215], v[214:215]
	v_pk_mov_b32 v[108:109], v[92:93], v[90:91] op_sel:[1,0]
	v_mov_b32_e32 v93, v91
	v_pk_mov_b32 v[90:91], v[102:103], v[100:101] op_sel:[1,0]
	v_mov_b32_e32 v103, v101
	v_mul_f32_e32 v107, v225, v225
	v_mul_f32_e32 v104, v219, v219
	v_mul_f32_e32 v106, v221, v221
	v_pk_add_f32 v[92:93], v[108:109], v[92:93]
	v_pk_add_f32 v[90:91], v[90:91], v[102:103]
	v_mul_f32_e32 v89, v224, v224
	v_mul_f32_e32 v110, v222, v222
	v_mul_f32_e32 v111, v223, v223
	v_pk_fma_f32 v[100:101], v[218:219], v[218:219], v[104:105] op_sel_hi:[1,1,0]
	v_pk_fma_f32 v[104:105], v[220:221], v[220:221], v[106:107] op_sel_hi:[1,1,0]
	v_pk_add_f32 v[92:93], v[92:93], v[92:93] op_sel:[0,1] op_sel_hi:[1,0]
	v_pk_add_f32 v[90:91], v[90:91], v[90:91] op_sel:[0,1] op_sel_hi:[1,0]
	v_mov_b32_e32 v101, v89
	v_mov_b32_e32 v105, v107
	v_mov_b32_e32 v93, v110
	v_mov_b32_e32 v91, v111
	v_pk_add_f32 v[100:101], v[100:101], v[104:105]
	v_pk_add_f32 v[90:91], v[92:93], v[90:91]
	s_nop 0
	v_pk_add_f32 v[90:91], v[90:91], v[100:101]
	s_nop 0
	v_add_f32_e32 v89, v90, v91
	s_nop 1
	v_add_f32_dpp v89, v89, v89 quad_perm:[1,0,3,2] row_mask:0xf bank_mask:0xf bound_ctrl:1
	s_nop 1
	v_add_f32_dpp v89, v89, v89 quad_perm:[2,3,0,1] row_mask:0xf bank_mask:0xf bound_ctrl:1
	s_nop 1
	v_add_f32_dpp v89, v89, v89 row_half_mirror row_mask:0xf bank_mask:0xf bound_ctrl:1
	s_nop 1
	v_add_f32_dpp v89, v89, v89 row_mirror row_mask:0xf bank_mask:0xf bound_ctrl:1
	s_nop 0
	v_readlane_b32 s0, v89, 16
	v_readlane_b32 s28, v89, 48
	v_readlane_b32 s26, v89, 0
	v_readlane_b32 s27, v89, 32
	v_mov_b32_e32 v90, s0
	v_mov_b32_e32 v91, s28
	v_pk_add_f32 v[90:91], s[26:27], v[90:91]
	s_nop 0
	v_add_f32_e32 v89, v90, v91
	v_fmamk_f32 v89, v89, 0x3a800000, v88
	v_rsq_f32_e32 v90, v89
	v_lshl_add_u64 v[66:67], v[64:65], 0, s[42:43]
	v_pk_mul_f32 v[92:93], v[210:211], v[90:91] op_sel_hi:[1,0]
	v_pk_mul_f32 v[100:101], v[212:213], v[90:91] op_sel_hi:[1,0]
	v_pk_mul_f32 v[102:103], v[214:215], v[90:91] op_sel_hi:[1,0]
	v_pk_mul_f32 v[104:105], v[216:217], v[90:91] op_sel_hi:[1,0]
	v_pk_mul_f32 v[106:107], v[218:219], v[90:91] op_sel_hi:[1,0]
	v_pk_mul_f32 v[108:109], v[220:221], v[90:91] op_sel_hi:[1,0]
	v_pk_mul_f32 v[110:111], v[222:223], v[90:91] op_sel_hi:[1,0]
	v_pk_mul_f32 v[90:91], v[224:225], v[90:91] op_sel_hi:[1,0]
	v_pk_fma_f32 v[92:93], v[10:11], v[92:93], v[6:7]
	v_pk_fma_f32 v[100:101], v[12:13], v[100:101], v[8:9]
	v_pk_fma_f32 v[102:103], v[18:19], v[102:103], v[2:3]
	v_pk_fma_f32 v[104:105], v[20:21], v[104:105], v[4:5]
	v_pk_fma_f32 v[108:109], v[24:25], v[108:109], v[32:33]
	v_pk_fma_f32 v[106:107], v[22:23], v[106:107], v[30:31]
	v_pk_fma_f32 v[112:113], v[16:17], v[90:91], v[28:29]
	v_pk_fma_f32 v[110:111], v[14:15], v[110:111], v[26:27]
	v_cvt_pk_bf16_f32 v90, v92, v93
	v_cvt_pk_bf16_f32 v91, v100, v101
	v_cvt_pk_bf16_f32 v92, v102, v103
	v_cvt_pk_bf16_f32 v93, v104, v105
	s_nop 0
	global_store_dwordx4 v[66:67], v[90:93], off sc1
	s_nop 1
	v_cvt_pk_bf16_f32 v210, v210, v211
	v_cvt_pk_bf16_f32 v211, v212, v213
	v_cvt_pk_bf16_f32 v212, v214, v215
	v_cvt_pk_bf16_f32 v213, v216, v217
	v_lshl_add_u64 v[68:69], v[64:65], 0, s[44:45]
	global_store_dwordx4 v[64:65], v[210:213], off sc1
	s_nop 1
	v_cvt_pk_bf16_f32 v34, v106, v107
	v_cvt_pk_bf16_f32 v35, v108, v109
	v_cvt_pk_bf16_f32 v36, v110, v111
	v_cvt_pk_bf16_f32 v37, v112, v113
	v_lshl_add_u64 v[70:71], v[64:65], 0, s[46:47]
	global_store_dwordx4 v[68:69], v[34:37], off sc1
	s_nop 1
	v_cvt_pk_bf16_f32 v218, v218, v219
	v_cvt_pk_bf16_f32 v219, v220, v221
	v_cvt_pk_bf16_f32 v220, v222, v223
	v_cvt_pk_bf16_f32 v221, v224, v225
	s_nop 0
	global_store_dwordx4 v[70:71], v[218:221], off sc1
	s_nop 1
	v_lshl_add_u64 v[64:65], v[64:65], 0, s[76:77]
	s_waitcnt vmcnt(28)
	v_pk_mul_f32 v[90:91], v[228:229], v[228:229]
	v_pk_mul_f32 v[92:93], v[226:227], v[226:227]
	v_pk_mul_f32 v[100:101], v[232:233], v[232:233]
	v_pk_mul_f32 v[102:103], v[230:231], v[230:231]
	v_pk_mov_b32 v[108:109], v[92:93], v[90:91] op_sel:[1,0]
	v_mov_b32_e32 v93, v91
	v_pk_mov_b32 v[90:91], v[102:103], v[100:101] op_sel:[1,0]
	v_mov_b32_e32 v103, v101
	v_mul_f32_e32 v107, v241, v241
	v_mul_f32_e32 v104, v235, v235
	v_mul_f32_e32 v106, v237, v237
	v_pk_add_f32 v[92:93], v[108:109], v[92:93]
	v_pk_add_f32 v[90:91], v[90:91], v[102:103]
	v_mul_f32_e32 v89, v240, v240
	v_mul_f32_e32 v110, v238, v238
	v_mul_f32_e32 v111, v239, v239
	v_pk_fma_f32 v[100:101], v[234:235], v[234:235], v[104:105] op_sel_hi:[1,1,0]
	v_pk_fma_f32 v[104:105], v[236:237], v[236:237], v[106:107] op_sel_hi:[1,1,0]
	v_pk_add_f32 v[92:93], v[92:93], v[92:93] op_sel:[0,1] op_sel_hi:[1,0]
	v_pk_add_f32 v[90:91], v[90:91], v[90:91] op_sel:[0,1] op_sel_hi:[1,0]
	v_mov_b32_e32 v101, v89
	v_mov_b32_e32 v105, v107
	v_mov_b32_e32 v93, v110
	v_mov_b32_e32 v91, v111
	v_pk_add_f32 v[100:101], v[100:101], v[104:105]
	v_pk_add_f32 v[90:91], v[92:93], v[90:91]
	s_nop 0
	v_pk_add_f32 v[90:91], v[90:91], v[100:101]
	s_nop 0
	v_add_f32_e32 v89, v90, v91
	s_nop 1
	v_add_f32_dpp v89, v89, v89 quad_perm:[1,0,3,2] row_mask:0xf bank_mask:0xf bound_ctrl:1
	s_nop 1
	v_add_f32_dpp v89, v89, v89 quad_perm:[2,3,0,1] row_mask:0xf bank_mask:0xf bound_ctrl:1
	s_nop 1
	v_add_f32_dpp v89, v89, v89 row_half_mirror row_mask:0xf bank_mask:0xf bound_ctrl:1
	s_nop 1
	v_add_f32_dpp v89, v89, v89 row_mirror row_mask:0xf bank_mask:0xf bound_ctrl:1
	s_nop 0
	v_readlane_b32 s0, v89, 16
	v_readlane_b32 s28, v89, 48
	v_readlane_b32 s26, v89, 0
	v_readlane_b32 s27, v89, 32
	v_mov_b32_e32 v90, s0
	v_mov_b32_e32 v91, s28
	v_pk_add_f32 v[90:91], s[26:27], v[90:91]
	s_nop 0
	v_add_f32_e32 v89, v90, v91
	v_fmamk_f32 v89, v89, 0x3a800000, v88
	v_rsq_f32_e32 v90, v89
	v_lshl_add_u64 v[66:67], v[64:65], 0, s[42:43]
	v_pk_mul_f32 v[92:93], v[226:227], v[90:91] op_sel_hi:[1,0]
	v_pk_mul_f32 v[100:101], v[228:229], v[90:91] op_sel_hi:[1,0]
	v_pk_mul_f32 v[102:103], v[230:231], v[90:91] op_sel_hi:[1,0]
	v_pk_mul_f32 v[104:105], v[232:233], v[90:91] op_sel_hi:[1,0]
	v_pk_mul_f32 v[106:107], v[234:235], v[90:91] op_sel_hi:[1,0]
	v_pk_mul_f32 v[108:109], v[236:237], v[90:91] op_sel_hi:[1,0]
	v_pk_mul_f32 v[110:111], v[238:239], v[90:91] op_sel_hi:[1,0]
	v_pk_mul_f32 v[90:91], v[240:241], v[90:91] op_sel_hi:[1,0]
	v_pk_fma_f32 v[92:93], v[10:11], v[92:93], v[6:7]
	v_pk_fma_f32 v[100:101], v[12:13], v[100:101], v[8:9]
	v_pk_fma_f32 v[102:103], v[18:19], v[102:103], v[2:3]
	v_pk_fma_f32 v[104:105], v[20:21], v[104:105], v[4:5]
	v_pk_fma_f32 v[108:109], v[24:25], v[108:109], v[32:33]
	v_pk_fma_f32 v[106:107], v[22:23], v[106:107], v[30:31]
	v_pk_fma_f32 v[112:113], v[16:17], v[90:91], v[28:29]
	v_pk_fma_f32 v[110:111], v[14:15], v[110:111], v[26:27]
	v_cvt_pk_bf16_f32 v90, v92, v93
	v_cvt_pk_bf16_f32 v91, v100, v101
	v_cvt_pk_bf16_f32 v92, v102, v103
	v_cvt_pk_bf16_f32 v93, v104, v105
	s_nop 0
	global_store_dwordx4 v[66:67], v[90:93], off sc1
	s_nop 1
	v_cvt_pk_bf16_f32 v226, v226, v227
	v_cvt_pk_bf16_f32 v227, v228, v229
	v_cvt_pk_bf16_f32 v228, v230, v231
	v_cvt_pk_bf16_f32 v229, v232, v233
	v_lshl_add_u64 v[68:69], v[64:65], 0, s[44:45]
	global_store_dwordx4 v[64:65], v[226:229], off sc1
	s_nop 1
	v_cvt_pk_bf16_f32 v34, v106, v107
	v_cvt_pk_bf16_f32 v35, v108, v109
	v_cvt_pk_bf16_f32 v36, v110, v111
	v_cvt_pk_bf16_f32 v37, v112, v113
	v_lshl_add_u64 v[70:71], v[64:65], 0, s[46:47]
	global_store_dwordx4 v[68:69], v[34:37], off sc1
	s_nop 1
	v_cvt_pk_bf16_f32 v234, v234, v235
	v_cvt_pk_bf16_f32 v235, v236, v237
	v_cvt_pk_bf16_f32 v236, v238, v239
	v_cvt_pk_bf16_f32 v237, v240, v241
	s_nop 0
	global_store_dwordx4 v[70:71], v[234:237], off sc1
	s_nop 1
	s_add_i32 s4, s4, s6
	v_lshl_add_u64 v[58:59], v[58:59], 0, s[22:23]
	s_cmpk_gt_i32 s4, 0x3fff
	v_lshl_add_u64 v[60:61], v[60:61], 0, s[36:37]
	s_cbranch_scc0 .LBB0_157
